# state pre-touch P7: last 16 prompt chunk-halves touch state_ssm (1 dword per 64B) so the sample part reads it from the memory-side cache
# speedup vs baseline: 1.0030x; 1.0015x over previous
; template <int DK, int MODE>
; __device__ void phase_rec(const Params& p, unsigned char* smem, const int rep_p, const int rep_s) {
;   for (int it0 = blockIdx.x; it0 < 256 * rep_p; it0 += gridDim.x) {
;     const int blk = it0 & 255;
;     const int item = (MODE == 0) ? (((blk & 7) * 4 + (blk >> 6)) * 8 + ((blk >> 3) & 7))
;                                  : (((blk & 7) * 8 + (blk >> 5)) * 4 + ((blk >> 3) & 3));
;     rec_prompt_item<DK, MODE>(p, item, smem);
;   }
;   rec_sample_loop<DK, MODE>(p, smem, rep_s);
; template <int PH>
; __device__ __forceinline__ void run_phase(Params p, unsigned char* smem, const int wvs) {
;     ...
;   if (PH == 7) phase_rec<128, 1>(p, smem, rep, 1 + (int)((p.dup >> (PH + 16)) & 1));
.LBB0_1703:
	s_cmp_lt_i32 s86, 8
	s_cselect_b64 s[0:1], -1, 0
	s_cmp_gt_i32 s88, 6
	s_cselect_b64 s[2:3], -1, 0
	s_and_b64 s[0:1], s[0:1], s[2:3]
	s_andn2_b64 vcc, exec, s[0:1]
	s_cbranch_vccnz .LBB0_2005
	v_readlane_b32 s0, v255, 0
	v_readlane_b32 s1, v255, 1
	s_load_dwordx4 s[92:95], s[0:1], 0x78
	s_load_dwordx2 s[2:3], s[0:1], 0x98
	s_load_dwordx2 s[82:83], s[0:1], 0x18
	s_mov_b64 s[24:25], 0
	s_add_u32 s22, s84, s24
	s_addc_u32 s23, s85, s25
	s_lshl_b64 s[4:5], s[24:25], 2
	s_waitcnt lgkmcnt(0)
	s_add_u32 s80, s2, s4
	v_readlane_b32 s2, v255, 6
	s_waitcnt vmcnt(1)
	v_mbcnt_lo_u32_b32 v0, -1, 0
	v_mbcnt_hi_u32_b32 v142, -1, v0
	s_addc_u32 s81, s3, s5
	v_lshl_add_u32 v72, s2, 6, v142
	s_lshl_b32 s79, s2, 12
	s_and_b32 s32, s78, 0xff
	s_lshl_b32 s32, s32, 19
	s_add_u32 s79, s79, s32
	s_movk_i32 s75, -48
	s_lshl_b32 s2, s90, 1
	s_and_b32 s50, s2, 0x100
	s_addk_i32 s50, 0x100
	s_mov_b64 s[0:1], 0
	v_ashrrev_i32_e32 v254, 31, v72
	s_cmp_lt_i32 s78, s50
	v_and_b32_e32 v148, 63, v142
	v_and_b32_e32 v252, 15, v142
	v_bfe_u32 v253, v142, 4, 2
	s_cbranch_scc1 .LBB0_1706
	v_ashrrev_i32_e32 v143, 6, v72
	v_and_b32_e32 v87, 63, v142
	v_and_b32_e32 v33, 15, v142
	v_bfe_u32 v34, v142, 4, 2
	v_lshlrev_b32_e32 v73, 4, v143
	s_andn2_b64 vcc, exec, s[0:1]
	v_lshlrev_b32_e32 v194, 3, v142
	s_cbranch_vccz .LBB0_1707
	s_branch .LBB0_1736

; template <int DK, int MODE>
; __device__ void rec_prompt_item(const Params& p, const int item, unsigned char* smem) {
;     ...
; #pragma unroll
;     for (int mf = 0; mf < MF; ++mf)
; #pragma unroll
;       for (int nf = 0; nf < 4; ++nf) {
;         u32x2 o;
;         o.x = pack2(S[mf][nf][0], S[mf][nf][1]);
;         o.y = pack2(S[mf][nf][2], S[mf][nf][3]);
;         *(u32x2*)(STs + (16 * nf + l15) * QS + (dw + 16 * mf + 4 * g) * 2) = o;
;       }
;     u16 gzc[2][4];
; #pragma unroll
;     for (int x = 0; x < 2; ++x)
; #pragma unroll
;       for (int r = 0; r < 4; ++r) gzc[x][r] = gz[par][x][r];
;     __syncthreads();
;     if (c + NSET < 32) PF_ISSUE(par, r0 + 64 * NSET)
.LBB0_1713:
	s_or_b64 exec, exec, s[0:1]
	s_cmp_lt_u32 s33, 30
	s_cselect_b64 s[46:47], -1, 0
	s_cmp_gt_u32 s33, 29
	v_cvt_pk_bf16_f32 v56, v52, v53
	v_cvt_pk_bf16_f32 v57, v54, v55
	v_cvt_pk_bf16_f32 v58, v48, v49
	v_cvt_pk_bf16_f32 v59, v50, v51
	s_cselect_b64 s[0:1], -1, 0
	ds_write2st64_b64 v190, v[56:57], v[58:59] offset0:72 offset1:81
	v_cvt_pk_bf16_f32 v56, v44, v45
	v_cvt_pk_bf16_f32 v57, v46, v47
	v_cvt_pk_bf16_f32 v58, v40, v41
	v_cvt_pk_bf16_f32 v59, v42, v43
	s_and_b64 vcc, exec, s[0:1]
	v_lshl_add_u64 v[132:133], v[100:101], 0, s[24:25]
	v_lshl_add_u64 v[130:131], v[104:105], 0, s[24:25]
	v_lshl_add_u64 v[128:129], v[106:107], 0, s[24:25]
	v_lshl_add_u64 v[126:127], v[90:91], 0, s[24:25]
	v_lshl_add_u64 v[124:125], v[92:93], 0, s[24:25]
	v_lshl_add_u64 v[122:123], v[96:97], 0, s[24:25]
	v_lshl_add_u64 v[120:121], v[98:99], 0, s[24:25]
	s_waitcnt vmcnt(18)
	v_mov_b32_e32 v227, v231
	v_mov_b32_e32 v225, v232
	v_mov_b32_e32 v223, v233
	v_mov_b32_e32 v221, v234
	v_mov_b32_e32 v226, v140
	v_mov_b32_e32 v224, v138
	v_mov_b32_e32 v222, v136
	v_mov_b32_e32 v220, v134
	ds_write2st64_b64 v190, v[56:57], v[58:59] offset0:90 offset1:99
	s_waitcnt lgkmcnt(0)
	s_barrier
	s_add_i32 s75, s75, 1
	s_sub_u32 s32, s75, 1
	s_cmp_gt_u32 s32, 15
	s_cbranch_scc1 .Lpt7a_skip
	s_lshl_b32 s32, s32, 15
	s_add_u32 s32, s32, s79
	v_mbcnt_lo_u32_b32 v254, -1, 0
	v_mbcnt_hi_u32_b32 v254, -1, v254
	v_lshl_add_u32 v254, v254, 6, s32
	global_load_dword v254, v254, s[82:83]
.Lpt7a_skip:
	s_cbranch_vccnz .LBB0_1715
	v_add_co_u32_e32 v0, vcc, 0x1e3a2000, v132
	v_lshl_add_u64 v[56:57], v[118:119], 0, s[24:25]
	s_nop 0
	v_addc_co_u32_e32 v1, vcc, 0, v133, vcc
	v_add_co_u32_e32 v4, vcc, 0x1e3a1000, v132
	s_add_u32 s48, s71, s24
	s_nop 0
	v_addc_co_u32_e32 v5, vcc, 0, v133, vcc
	v_add_co_u32_e32 v8, vcc, 0x1e3a2000, v130
	global_load_dwordx4 v[0:3], v[0:1], off
	s_nop 0
	global_load_dwordx4 v[4:7], v[4:5], off offset:2048
	v_addc_co_u32_e32 v9, vcc, 0, v131, vcc
	v_add_co_u32_e32 v12, vcc, 0x1e3a1000, v130
	s_addc_u32 s49, s72, s25
	s_nop 0
	v_addc_co_u32_e32 v13, vcc, 0, v131, vcc
	v_add_co_u32_e32 v16, vcc, 0x1e3a2000, v128
	global_load_dwordx4 v[8:11], v[8:9], off
	s_nop 0
	global_load_dwordx4 v[12:15], v[12:13], off offset:2048
	v_addc_co_u32_e32 v17, vcc, 0, v129, vcc
	v_add_co_u32_e32 v58, vcc, 0x26ee6000, v56
	global_load_dwordx4 v[16:19], v[16:17], off
	s_nop 0
	v_addc_co_u32_e32 v59, vcc, 0, v57, vcc
	v_add_co_u32_e32 v56, vcc, 0x26cc6000, v56
	s_nop 1
	v_addc_co_u32_e32 v57, vcc, 0, v57, vcc
	global_load_dword v205, v[58:59], off
	global_load_dword v206, v[56:57], off
	v_lshl_add_u64 v[56:57], v[116:117], 0, s[24:25]
	v_add_co_u32_e32 v58, vcc, s60, v56
	global_load_dword v207, v75, s[48:49]
	s_nop 0
	v_addc_co_u32_e32 v59, vcc, 0, v57, vcc
	v_add_co_u32_e32 v56, vcc, s61, v56
	s_nop 1
	v_addc_co_u32_e32 v57, vcc, 0, v57, vcc
	global_load_dword v208, v[58:59], off
	global_load_dword v209, v[56:57], off
	v_add_co_u32_e32 v56, vcc, s62, v126
	s_nop 1
	v_addc_co_u32_e32 v57, vcc, 0, v127, vcc
	v_add_co_u32_e32 v58, vcc, s62, v124
	s_nop 1
	v_addc_co_u32_e32 v59, vcc, 0, v125, vcc
	v_add_co_u32_e32 v60, vcc, 0x45c6000, v122
	s_nop 1
	v_addc_co_u32_e32 v61, vcc, 0, v123, vcc
	v_add_co_u32_e32 v62, vcc, 0x45c6000, v120
	s_nop 1
	v_addc_co_u32_e32 v63, vcc, 0, v121, vcc
	global_load_ushort v220, v[56:57], off
	global_load_ushort v221, v[56:57], off offset:32
	global_load_ushort v222, v[58:59], off
	global_load_ushort v223, v[58:59], off offset:32
	global_load_ushort v224, v[60:61], off
	global_load_ushort v225, v[60:61], off offset:32
	global_load_ushort v226, v[62:63], off
	global_load_ushort v227, v[62:63], off offset:32

; template <int DK, int MODE>
; __device__ void rec_prompt_item(const Params& p, const int item, unsigned char* smem) {
;     ...
; #pragma unroll
;     for (int mf = 0; mf < MF; ++mf)
; #pragma unroll
;       for (int nf = 0; nf < 4; ++nf) {
;         u32x2 o;
;         o.x = pack2(S[mf][nf][0], S[mf][nf][1]);
;         o.y = pack2(S[mf][nf][2], S[mf][nf][3]);
;         *(u32x2*)(STs + (16 * nf + l15) * QS + (dw + 16 * mf + 4 * g) * 2) = o;
;       }
;     u16 gzc[2][4];
; #pragma unroll
;     for (int x = 0; x < 2; ++x)
; #pragma unroll
;       for (int r = 0; r < 4; ++r) gzc[x][r] = gz[par][x][r];
;     __syncthreads();
;     if (c + NSET < 32) PF_ISSUE(par, r0 + 64 * NSET)
.LBB0_1725:
	s_or_b64 exec, exec, s[48:49]
	v_cvt_pk_bf16_f32 v56, v40, v41
	v_cvt_pk_bf16_f32 v57, v42, v43
	v_cvt_pk_bf16_f32 v58, v44, v45
	v_cvt_pk_bf16_f32 v59, v46, v47
	ds_write2st64_b64 v190, v[56:57], v[58:59] offset0:72 offset1:81
	v_cvt_pk_bf16_f32 v56, v52, v53
	v_cvt_pk_bf16_f32 v57, v54, v55
	v_cvt_pk_bf16_f32 v58, v48, v49
	v_cvt_pk_bf16_f32 v59, v50, v51
	s_andn2_b64 vcc, exec, s[46:47]
	s_waitcnt vmcnt(8)
	v_mov_b32_e32 v242, v215
	v_mov_b32_e32 v240, v216
	v_mov_b32_e32 v234, v217
	v_mov_b32_e32 v232, v218
	v_mov_b32_e32 v241, v219
	v_mov_b32_e32 v239, v228
	v_mov_b32_e32 v233, v229
	v_mov_b32_e32 v231, v230
	ds_write2st64_b64 v190, v[56:57], v[58:59] offset0:90 offset1:99
	s_waitcnt lgkmcnt(0)
	s_barrier
	s_add_i32 s75, s75, 1
	s_sub_u32 s32, s75, 1
	s_cmp_gt_u32 s32, 15
	s_cbranch_scc1 .Lpt7b_skip
	s_lshl_b32 s32, s32, 15
	s_add_u32 s32, s32, s79
	v_mbcnt_lo_u32_b32 v254, -1, 0
	v_mbcnt_hi_u32_b32 v254, -1, v254
	v_lshl_add_u32 v254, v254, 6, s32
	global_load_dword v254, v254, s[82:83]
.Lpt7b_skip:
	s_cbranch_vccnz .LBB0_1727
	v_add_co_u32_e32 v20, vcc, 0x1e422000, v132
	v_lshl_add_u64 v[56:57], v[88:89], 0, s[24:25]
	s_nop 0
	v_addc_co_u32_e32 v21, vcc, 0, v133, vcc
	v_add_co_u32_e32 v24, vcc, 0x1e421000, v132
	s_add_u32 s46, s69, s24
	s_nop 0
	v_addc_co_u32_e32 v25, vcc, 0, v133, vcc
	v_add_co_u32_e32 v28, vcc, 0x1e422000, v130
	global_load_dwordx4 v[20:23], v[20:21], off
	s_nop 0
	global_load_dwordx4 v[24:27], v[24:25], off offset:2048
	v_addc_co_u32_e32 v29, vcc, 0, v131, vcc
	v_add_co_u32_e32 v32, vcc, 0x1e421000, v130
	s_addc_u32 s47, s70, s25
	s_nop 0
	v_addc_co_u32_e32 v33, vcc, 0, v131, vcc
	v_add_co_u32_e32 v36, vcc, 0x1e422000, v128
	global_load_dwordx4 v[28:31], v[28:29], off
	s_nop 0
	global_load_dwordx4 v[32:35], v[32:33], off offset:2048
	v_addc_co_u32_e32 v37, vcc, 0, v129, vcc
	v_add_co_u32_e32 v58, vcc, 0x26ee2000, v56
	global_load_dwordx4 v[36:39], v[36:37], off
	s_nop 0
	v_addc_co_u32_e32 v59, vcc, 0, v57, vcc
	v_add_co_u32_e32 v56, vcc, 0x26cc2000, v56
	s_nop 1
	v_addc_co_u32_e32 v57, vcc, 0, v57, vcc
	global_load_dword v210, v[58:59], off
	global_load_dword v211, v[56:57], off
	v_lshl_add_u64 v[56:57], v[86:87], 0, s[24:25]
	v_add_co_u32_e32 v58, vcc, s64, v56
	global_load_dword v212, v75, s[46:47]
	s_nop 0
	v_addc_co_u32_e32 v59, vcc, 0, v57, vcc
	v_add_co_u32_e32 v56, vcc, s65, v56
	s_nop 1
	v_addc_co_u32_e32 v57, vcc, 0, v57, vcc
	global_load_dword v213, v[58:59], off
	global_load_dword v214, v[56:57], off
	v_add_co_u32_e32 v56, vcc, s66, v126
	s_nop 1
	v_addc_co_u32_e32 v57, vcc, 0, v127, vcc
	v_add_co_u32_e32 v58, vcc, s66, v124
	s_nop 1
	v_addc_co_u32_e32 v59, vcc, 0, v125, vcc
	v_add_co_u32_e32 v60, vcc, 0x4688000, v122
	s_nop 1
	v_addc_co_u32_e32 v61, vcc, 0, v123, vcc
	v_add_co_u32_e32 v62, vcc, 0x4688000, v120
	s_nop 1
	v_addc_co_u32_e32 v63, vcc, 0, v121, vcc
	global_load_ushort v231, v[56:57], off
	global_load_ushort v232, v[56:57], off offset:32
	global_load_ushort v233, v[58:59], off
	global_load_ushort v234, v[58:59], off offset:32
	global_load_ushort v239, v[60:61], off
	global_load_ushort v240, v[60:61], off offset:32
	global_load_ushort v241, v[62:63], off
	global_load_ushort v242, v[62:63], off offset:32

.LBB0_1736:
	v_readlane_b32 s0, v255, 0
	v_readlane_b32 s1, v255, 1
	v_mov_b32 v74, 0
	s_load_dwordx2 s[46:47], s[0:1], 0x18
	v_ashrrev_i32_e32 v75, 31, v74
	v_lshl_add_u64 v[0:1], v[74:75], 1, s[22:23]
	s_mov_b64 s[0:1], 0x1e2a2000
	v_lshl_add_u64 v[76:77], v[0:1], 0, s[0:1]
	s_mov_b64 s[0:1], 0x4442000
	v_lshl_add_u64 v[78:79], v[0:1], 0, s[0:1]
	v_lshl_add_u64 v[0:1], v[74:75], 2, s[22:23]
	s_mov_b64 s[0:1], 0x26cc2000
	v_lshl_add_u64 v[80:81], v[0:1], 0, s[0:1]
	s_mov_b64 s[0:1], 0x26ee2000
	v_lshl_add_u64 v[82:83], v[0:1], 0, s[0:1]
	s_lshr_b32 s0, s90, 11
	s_and_b32 s33, s0, 0x1000
	s_addk_i32 s33, 0x1000
	s_cmp_lt_i32 s78, s33
	s_cselect_b64 s[0:1], -1, 0
	s_cmp_ge_i32 s78, s33
	v_and_b32_e32 v35, 15, v72
	s_cbranch_scc1 .LBB0_1746
	s_and_b32 s2, s78, 0xfff
	v_add_u32_e32 v26, s2, v74
	v_add_u32_e32 v27, s78, v74
	s_movk_i32 s2, 0xffe0
	v_bfi_b32 v0, s2, v26, v27
	v_ashrrev_i32_e32 v1, 31, v0
	v_lshlrev_b64 v[0:1], 15, v[0:1]
	v_lshl_add_u32 v4, v34, 2, v73
	s_waitcnt lgkmcnt(0)
	v_lshl_add_u64 v[2:3], s[46:47], 0, v[0:1]
	v_lshlrev_b32_e32 v0, 2, v35
	v_mov_b32_e32 v1, 0
	v_ashrrev_i32_e32 v5, 31, v4
	v_lshl_add_u64 v[2:3], v[2:3], 0, v[0:1]
	v_lshlrev_b64 v[6:7], 8, v[4:5]
	v_lshl_add_u64 v[20:21], v[2:3], 0, v[6:7]
	v_or_b32_e32 v6, 1, v4
	v_ashrrev_i32_e32 v7, 31, v6
	v_lshlrev_b64 v[6:7], 8, v[6:7]
	v_lshl_add_u64 v[22:23], v[2:3], 0, v[6:7]
	v_or_b32_e32 v6, 2, v4
	v_or_b32_e32 v4, 3, v4
	v_ashrrev_i32_e32 v7, 31, v6
	v_ashrrev_i32_e32 v5, 31, v4
	v_lshlrev_b64 v[6:7], 8, v[6:7]
	v_lshlrev_b64 v[4:5], 8, v[4:5]
	v_lshl_add_u64 v[24:25], v[2:3], 0, v[6:7]
	v_lshl_add_u64 v[2:3], v[2:3], 0, v[4:5]
	global_load_dword v4, v[20:21], off
	global_load_dword v5, v[22:23], off
	global_load_dword v8, v[20:21], off offset:64
	global_load_dword v9, v[22:23], off offset:64
	global_load_dword v12, v[20:21], off offset:128
	global_load_dword v13, v[22:23], off offset:128
	global_load_dword v17, v[22:23], off offset:192
	global_load_dword v16, v[20:21], off offset:192
	global_load_dword v6, v[24:25], off
	global_load_dword v7, v[2:3], off
	global_load_dword v10, v[24:25], off offset:64
	global_load_dword v11, v[2:3], off offset:64
	global_load_dword v14, v[24:25], off offset:128
	global_load_dword v15, v[2:3], off offset:128
	global_load_dword v19, v[2:3], off offset:192
	global_load_dword v18, v[24:25], off offset:192
	v_ashrrev_i32_e32 v0, 2, v26
	v_and_b32_e32 v28, -8, v0
	s_movk_i32 s2, 0x100
	v_and_b32_e32 v24, 31, v27
	v_add_u32_e32 v27, 0x4000, v28
	v_cmp_gt_i32_e32 vcc, s2, v72
	v_mov_b32_e32 v0, v1
	v_mov_b32_e32 v2, v1
	v_mov_b32_e32 v3, v1
	s_and_saveexec_b64 s[2:3], vcc
	s_cbranch_execz .LBB0_1739
	v_mov_b32_e32 v2, 0
	v_add_u32_e32 v2, v72, v2
	v_and_b32_e32 v2, 0xffffff80, v2
	v_sub_u32_e32 v20, v72, v2
	v_mov_b32_e32 v2, 11
	v_lshrrev_b16_sdwa v2, v2, sext(v20) dst_sel:DWORD dst_unused:UNUSED_PAD src0_sel:DWORD src1_sel:BYTE_0
	v_and_b32_e32 v2, 15, v2
	v_add_u16_e32 v21, v20, v2
	v_mov_b32_e32 v2, 4
	v_ashrrev_i16_sdwa v2, v2, sext(v21) dst_sel:DWORD dst_unused:UNUSED_PAD src0_sel:DWORD src1_sel:BYTE_0
	v_add_u32_e32 v22, 0x7f, v72
	s_movk_i32 s4, 0xff
	v_add_u32_sdwa v2, v27, sext(v2) dst_sel:DWORD dst_unused:UNUSED_PAD src0_sel:DWORD src1_sel:WORD_0
	v_mov_b32_e32 v23, 0x800
	v_mov_b32_e32 v25, 0xc00
	v_cmp_gt_u32_e32 vcc, s4, v22
	v_lshlrev_b32_e32 v0, 5, v24
	v_ashrrev_i32_e32 v3, 31, v2
	v_cndmask_b32_e32 v22, v23, v25, vcc
	s_movk_i32 s4, 0x380
	v_lshlrev_b64 v[2:3], 13, v[2:3]
	v_and_or_b32 v0, v0, s4, v22
	v_lshl_add_u64 v[2:3], v[76:77], 0, v[2:3]
	v_lshlrev_b32_e32 v0, 1, v0
	v_lshl_add_u64 v[0:1], v[2:3], 0, v[0:1]
	v_and_b32_e32 v2, 0xf0, v21
	v_sub_u16_e32 v2, v20, v2
	v_mov_b32_e32 v3, 3
	v_lshlrev_b32_sdwa v2, v3, sext(v2) dst_sel:DWORD dst_unused:UNUSED_PAD src0_sel:DWORD src1_sel:BYTE_0
	v_ashrrev_i32_e32 v3, 31, v2
	v_lshl_add_u64 v[0:1], v[2:3], 1, v[0:1]
	global_load_dwordx4 v[0:3], v[0:1], off

; template <int DK, int MODE>
; __device__ void rec_sample_loop(const Params& p, unsigned char* smem, const int rep) {
;   constexpr int SET_FLOATS = 8 * DK + 8 * DK + 512 + 64 + 4096 + 64 + (DK * 8 + 64 * 8) / 2;
;   const int tid = (int)p.tidx, lane = tid & 63, w = tid >> 6;
;   const int l15 = lane & 15, g = lane >> 4;
;   constexpr int CPR = DK / 8;
;   constexpr int DPW = DK / 8;
;   constexpr int NB = DPW / 16;
;   const int dbase = w * DPW;
;   const int pitch = (MODE == 0) ? 512 : 64;
;   int vz;
;   asm volatile("v_mov_b32 %0, 0" : "=v"(vz));
;   const u16* src = ((MODE == 0) ? (const u16*)(p.ws + OFF_PROJ) : (const u16*)(p.ws + OFF_XBCC)) + vz;
;   const int sstride = (MODE == 0) ? PROJ_LD : 4096;
;   const u16* gsrc = (const u16*)(p.ws + OFF_PROJ) + vz;
;   const float* dtv = (const float*)(p.ws + OFF_DT) + vz;
;   const float* cumv = (const float*)(p.ws + OFF_CUM) + vz;
;   u16* aout = (u16*)(p.ws + OFF_A2);
;   float* parts = (float*)(p.ws + OFF_PARTS);
;   u32x4 rqk[2] = {(u32x4){0u, 0u, 0u, 0u}, (u32x4){0u, 0u, 0u, 0u}}, rv[2] = {(u32x4){0u, 0u, 0u, 0u}, (u32x4){0u, 0u, 0u, 0u}};
;   f32x4 sv[2][NB][4];
;   u16 gzs[2] = {0, 0};
;   float pcu[2] = {0.f, 0.f}, pvc[2] = {0.f, 0.f}, pvu[2] = {1.f, 1.f}, pvl[2] = {0.f, 0.f};
;   const int nitems = 4096 * rep;
;   const int G = (int)gridDim.x;
;   if ((int)blockIdx.x < nitems) SAMPLE_ISSUE(0, ((int)blockIdx.x & 4095) + vz)
;   for (int itb = blockIdx.x; itb < nitems; itb += 2 * G) {
.LBB0_1747:
	v_mov_b32_e32 v27, 0
	v_add_u32_e32 v27, v72, v27
	v_and_b32_e32 v27, 0xffffff80, v27
	v_sub_u32_e32 v29, v72, v27
	v_mov_b32_e32 v27, 11
	v_lshrrev_b16_sdwa v27, v27, sext(v29) dst_sel:DWORD dst_unused:UNUSED_PAD src0_sel:DWORD src1_sel:BYTE_0
	v_and_b32_e32 v27, 15, v27
	v_add_u16_e32 v30, v29, v27
	v_mov_b32_e32 v27, 4
	v_ashrrev_i16_sdwa v27, v27, sext(v30) dst_sel:DWORD dst_unused:UNUSED_PAD src0_sel:DWORD src1_sel:BYTE_0
	v_and_b32_e32 v30, 0xf0, v30
	v_sub_u16_e32 v29, v29, v30
	v_lshlrev_b32_e32 v31, 2, v34
	v_add_u32_e32 v32, 0x7f, v72
	s_movk_i32 s4, 0xfe
	s_movk_i32 s6, 0xff
	s_waitcnt vmcnt(0)
	v_bfe_i32 v38, v29, 0, 8
	v_lshlrev_b32_e32 v29, 3, v72
	v_or_b32_e32 v28, v31, v73
	v_cmp_lt_u32_e64 s[4:5], s4, v32
	v_mov_b32_e32 v36, 0x800
	v_mov_b32_e32 v37, 0xc00
	v_cmp_gt_u32_e32 vcc, s6, v32
	v_and_b32_e32 v32, 56, v29
	v_mov_b32_e32 v29, 9
	v_cndmask_b32_e32 v128, v36, v37, vcc
	v_lshlrev_b32_sdwa v40, v29, sext(v27) dst_sel:DWORD dst_unused:UNUSED_PAD src0_sel:DWORD src1_sel:WORD_0
	v_or_b32_e32 v29, v33, v73
	v_or_b32_e32 v36, 1, v28
	v_lshlrev_b32_e32 v131, 4, v29
	v_ashrrev_i32_e32 v29, 31, v28
	v_ashrrev_i32_e32 v37, 31, v36
	v_lshlrev_b64 v[88:89], 8, v[28:29]
	v_lshlrev_b64 v[90:91], 8, v[36:37]
	v_or_b32_e32 v36, 2, v28
	v_or_b32_e32 v28, 3, v28
	v_ashrrev_i32_e32 v29, 31, v28
	v_writelane_b32 v255, s76, 9
	v_lshlrev_b64 v[94:95], 8, v[28:29]
	v_mov_b32_e32 v28, 0x1000
	v_writelane_b32 v255, s77, 10
	v_ashrrev_i32_e32 v37, 31, v36
	v_cndmask_b32_e64 v28, v28, 0, vcc
	v_cmp_gt_u32_e64 s[48:49], v33, v31
	v_lshlrev_b64 v[92:93], 8, v[36:37]
	v_add_u32_e32 v36, v28, v40
	v_mov_b32_e32 v28, 1
	v_writelane_b32 v255, s48, 7
	v_or_b32_e32 v29, 1, v31
	v_and_b32_e32 v42, 56, v194
	v_lshlrev_b32_sdwa v28, v28, sext(v27) dst_sel:DWORD dst_unused:UNUSED_PAD src0_sel:DWORD src1_sel:WORD_0
	v_writelane_b32 v255, s49, 8
	v_cmp_gt_u32_e64 s[48:49], v33, v29
	v_ashrrev_i32_e32 v129, 3, v72
	v_lshl_add_u32 v135, v38, 7, v28
	v_lshlrev_b32_e32 v28, 2, v42
	v_writelane_b32 v255, s48, 2
	v_lshlrev_b32_e32 v141, 5, v29
	v_or_b32_e32 v29, 2, v31
	v_lshl_or_b32 v136, v129, 8, v28
	v_lshlrev_b32_e32 v28, 1, v129
	v_writelane_b32 v255, s49, 3
	v_cmp_gt_u32_e64 s[48:49], v33, v29
	v_lshl_add_u32 v137, v42, 4, v28
	v_lshlrev_b32_e32 v28, 9, v142
	v_writelane_b32 v255, s48, 11
	v_lshlrev_b32_e32 v144, 5, v29
	v_or_b32_e32 v29, 3, v31
	v_and_b32_e32 v28, 0xe00, v28
	v_writelane_b32 v255, s49, 12
	v_cmp_gt_u32_e64 s[48:49], v33, v29
	v_lshlrev_b32_e32 v145, 5, v29
	v_lshlrev_b32_e32 v29, 2, v73
	v_lshlrev_b32_e32 v31, 4, v34
	v_lshl_add_u32 v138, v34, 5, v28
	v_add3_u32 v147, v28, v29, v31
	v_lshlrev_b32_e32 v28, 10, v34
	v_cmp_eq_u32_e64 s[42:43], 1, v34
	v_lshlrev_b32_e32 v140, 7, v34
	v_lshl_add_u32 v34, v143, 11, v28
	v_and_b32_e32 v28, 64, v142
	v_add_u32_e32 v28, 64, v28
	v_xor_b32_e32 v29, 32, v142
	v_cmp_lt_i32_e64 s[74:75], v29, v28
	v_lshlrev_b32_e32 v84, 3, v38
	v_lshlrev_b32_e32 v41, 5, v38
	v_cndmask_b32_e64 v31, v142, v29, s[74:75]
	v_xor_b32_e32 v29, 16, v142
	v_cmp_lt_i32_e64 s[74:75], v29, v28
	v_and_b32_e32 v43, 0x3fffffc0, v72
	v_lshlrev_b32_e32 v148, 2, v87
	v_cndmask_b32_e64 v37, v142, v29, s[74:75]
	v_xor_b32_e32 v29, 8, v142
	v_cmp_lt_i32_e64 s[74:75], v29, v28
	v_lshl_add_u32 v149, v43, 2, v148
	v_mov_b32_e32 v30, 0
	v_cndmask_b32_e64 v38, v142, v29, s[74:75]
	v_xor_b32_e32 v29, 4, v142
	v_cmp_lt_i32_e64 s[74:75], v29, v28
	v_lshlrev_b32_e32 v139, 2, v33
	s_add_u32 s0, s22, 0x11262000
	v_cndmask_b32_e64 v42, v142, v29, s[74:75]
	v_xor_b32_e32 v29, 2, v142
	v_cmp_lt_i32_e64 s[74:75], v29, v28
	s_movk_i32 s2, 0x100
	v_add_u32_e32 v39, -8, v72
	v_cndmask_b32_e64 v43, v142, v29, s[74:75]
	v_xor_b32_e32 v29, 1, v142
	v_cmp_lt_i32_e64 s[74:75], v29, v28
	v_mov_b32_e32 v28, 0x8600
	v_mad_u32_u24 v146, v33, 12, v139
	v_cndmask_b32_e64 v44, v142, v29, s[74:75]
	v_mov_b32_e32 v29, 0x7600
	v_cndmask_b32_e32 v45, v28, v29, vcc
	v_cmp_gt_i32_e32 vcc, 8, v72
	v_lshlrev_b32_e32 v28, 2, v35
	v_mov_b32_e32 v29, v30
	s_addc_u32 s1, s23, 0
	v_cmp_gt_i32_e64 s[2:3], s2, v72
	v_cmp_gt_i32_e64 s[6:7], 64, v72
	v_cmp_lt_i32_e64 s[8:9], 63, v72
	v_and_b32_e32 v86, 63, v72
	v_cmp_gt_i32_e64 s[10:11], 16, v72
	v_lshlrev_b32_e32 v130, 2, v72
	v_cmp_gt_u32_e64 s[12:13], 64, v72
	v_cmp_gt_u32_e64 s[16:17], 8, v33
	v_cmp_lt_u32_e64 s[18:19], 7, v33
	v_cmp_eq_u32_e64 s[24:25], 0, v33
	v_cmp_eq_u32_e64 s[26:27], 1, v33
	v_cmp_eq_u32_e64 s[28:29], 2, v33
	v_cmp_eq_u32_e64 s[30:31], 3, v33
	v_cmp_eq_u32_e64 s[34:35], 4, v33
	v_cmp_eq_u32_e64 s[36:37], 5, v33
	v_cmp_eq_u32_e64 s[38:39], 6, v33
	v_cmp_eq_u32_e64 s[40:41], 7, v33
	v_mad_i32_i24 v33, v33, -12, v146
	v_cndmask_b32_e32 v150, v39, v72, vcc
	s_waitcnt lgkmcnt(0)
	v_lshl_add_u64 v[72:73], s[46:47], 0, v[28:29]
	v_lshlrev_b32_e32 v151, 2, v31
	v_add_u32_e32 v35, v45, v40
	v_lshl_add_u64 v[28:29], s[80:81], 0, v[28:29]
	s_mov_b64 s[46:47], 0x15c00000
	v_mov_b32_e32 v31, v30
	s_add_u32 s82, s22, 0x15662000
	v_cmp_gt_u32_e64 s[14:15], 32, v87
	v_writelane_b32 v255, s48, 13
	s_mov_b32 s89, s78
	v_lshlrev_b32_e32 v152, 2, v37
	v_lshlrev_b32_e32 v153, 2, v38
	v_lshl_add_u64 v[98:99], v[28:29], 0, s[46:47]
	v_mov_b32_e32 v28, v30
	v_mov_b32_e32 v29, v30
	v_add_u32_e32 v157, v36, v41
	v_add_u32_e32 v158, v35, v41
	v_lshlrev_b32_e32 v100, 1, v32
	v_add_u32_e32 v159, v33, v34
	v_mov_b64_e32 v[34:35], v[30:31]
	v_mov_b64_e32 v[38:39], v[30:31]
	s_addc_u32 s83, s23, 0
	v_ashrrev_i32_e32 v85, 31, v84
	s_and_b64 s[44:45], s[14:15], s[16:17]
	v_cmp_gt_u32_e64 s[16:17], 16, v87
	v_lshlrev_b32_e32 v132, 5, v143
	v_add_u32_e32 v133, 0x4000, v143
	v_cmp_gt_u32_e64 s[20:21], 2, v87
	v_cmp_eq_u32_e64 s[22:23], 0, v87
	s_lshl_b32 s87, s96, 1
	v_writelane_b32 v255, s49, 14
	v_cmp_eq_u32_e64 s[52:53], 1, v143
	v_cmp_eq_u32_e64 s[54:55], 2, v143
	v_cmp_eq_u32_e64 s[56:57], 3, v143
	v_cmp_eq_u32_e64 s[58:59], 4, v143
	v_cmp_eq_u32_e64 s[60:61], 5, v143
	v_cmp_eq_u32_e64 s[62:63], 6, v143
	v_cmp_eq_u32_e64 s[64:65], 7, v143
	v_cmp_lt_i32_e64 s[66:67], -1, v143
	v_cmp_lt_i32_e64 s[68:69], 0, v143
	v_cmp_lt_i32_e64 s[70:71], 1, v143
	v_cmp_lt_i32_e64 s[72:73], 2, v143
	v_cmp_lt_i32_e64 s[74:75], 3, v143
	v_cndmask_b32_e32 v97, v81, v83, vcc
	v_cndmask_b32_e32 v96, v80, v82, vcc
	v_cmp_lt_i32_e64 s[76:77], 4, v143
	v_cmp_lt_i32_e64 s[78:79], 5, v143
	v_lshlrev_b32_e32 v154, 2, v42
	v_lshlrev_b32_e32 v155, 2, v43
	v_lshlrev_b32_e32 v156, 2, v44
	v_mov_b32_e32 v160, 1.0
	s_movk_i32 s91, 0x3080
	v_lshlrev_b32_e32 v102, 1, v86
	v_mov_b64_e32 v[32:33], v[28:29]
	v_mov_b64_e32 v[36:37], v[28:29]
	v_mov_b32_e32 v164, 0
	v_mov_b32_e32 v161, 0
	v_mov_b32_e32 v162, 0
	v_mov_b32_e32 v163, 0
	s_mov_b32 s51, s89
	v_cmp_lt_i32_e64 s[80:81], 6, v143
	s_branch .LBB0_1749
